# attention softmax row-max cross-quad reduction: ds_bpermute round trips replaced by v_permlane16/32_swap (VALU), 16 sites
# baseline (speedup 1.0000x reference)
.LBB0_216:
	v_mov_b64_e32 v[30:31], v[110:111]
	v_mov_b64_e32 v[26:27], v[106:107]
	v_mov_b64_e32 v[4:5], v[102:103]
	v_mov_b64_e32 v[0:1], v[98:99]
	v_mov_b64_e32 v[22:23], v[78:79]
	v_mov_b64_e32 v[18:19], v[74:75]
	v_mov_b64_e32 v[14:15], v[70:71]
	v_mov_b64_e32 v[10:11], v[54:55]
	v_mov_b32_e32 v134, v140
	v_mov_b64_e32 v[32:33], v[112:113]
	v_mov_b64_e32 v[28:29], v[108:109]
	v_mov_b64_e32 v[6:7], v[104:105]
	v_mov_b64_e32 v[2:3], v[100:101]
	v_mov_b64_e32 v[24:25], v[80:81]
	v_mov_b64_e32 v[20:21], v[76:77]
	v_mov_b64_e32 v[16:17], v[72:73]
	v_mov_b64_e32 v[12:13], v[56:57]
	v_mov_b32_e32 v135, v82
	s_cmpk_eq_i32 s28, 0x5000
	s_mov_b64 s[0:1], -1
	s_cbranch_scc1 .LBB0_215
	v_add_co_u32_e32 v54, vcc, 0x1000, v146
	v_mov_b32_e32 v102, v153
	s_nop 0
	v_addc_co_u32_e32 v55, vcc, 0, v147, vcc
	global_load_dwordx4 v[94:97], v[54:55], off
	global_load_dwordx4 v[86:89], v[54:55], off offset:1024
	global_load_dwordx4 v[90:93], v[54:55], off offset:2048
	global_load_dwordx4 v[82:85], v[54:55], off offset:3072
	v_add_co_u32_e32 v54, vcc, 0x1000, v144
	s_nop 1
	v_addc_co_u32_e32 v55, vcc, 0, v145, vcc
	global_load_dwordx4 v[78:81], v[54:55], off
	global_load_dwordx4 v[74:77], v[54:55], off offset:1024
	global_load_dwordx4 v[70:73], v[54:55], off offset:2048
	s_nop 0
	global_load_dwordx4 v[54:57], v[54:55], off offset:3072
	ds_read_b128 v[98:101], v102
	ds_read_b128 v[102:105], v102 offset:64
	s_waitcnt vmcnt(15) lgkmcnt(1)
	v_mfma_f32_16x16x32_bf16 v[106:109], v[62:65], v[98:101], 0
	s_waitcnt vmcnt(13)
	v_mfma_f32_16x16x32_bf16 v[98:101], v[66:69], v[98:101], 0
	s_waitcnt vmcnt(12) lgkmcnt(0)
	v_mfma_f32_16x16x32_bf16 v[98:101], v[50:53], v[102:105], v[98:101]
	v_mfma_f32_16x16x32_bf16 v[112:115], v[58:61], v[102:105], v[106:109]
	s_nop 6
	v_mul_f32_e32 v109, 0x3e38aa3b, v100
	v_mul_f32_e32 v108, 0x3e38aa3b, v101
	v_mul_f32_e32 v123, 0x3e38aa3b, v112
	v_mul_f32_e32 v111, 0x3e38aa3b, v98
	v_mul_f32_e32 v122, 0x3e38aa3b, v113
	v_mul_f32_e32 v110, 0x3e38aa3b, v99
	v_mul_f32_e32 v113, 0x3e38aa3b, v114
	v_mul_f32_e32 v112, 0x3e38aa3b, v115
	v_max_f32_e32 v100, v109, v108
	v_max_f32_e32 v98, v123, v122
	v_max_f32_e32 v99, v113, v112
	v_max3_f32 v100, v111, v110, v100
	v_max3_f32 v98, v98, v99, v100
	v_and_b32_e32 v100, 64, v220
	v_xor_b32_e32 v99, 16, v220
	v_add_u32_e32 v100, 64, v100
	v_cmp_lt_i32_e32 vcc, v99, v100
	s_nop 1
	v_cndmask_b32_e32 v99, v220, v99, vcc
	v_lshlrev_b32_e32 v154, 2, v99
	v_mov_b32_e32 v99, v98
	s_nop 1
	v_permlane16_swap_b32_e32 v99, v98
	s_waitcnt lgkmcnt(0)
	v_max_f32_e32 v99, v99, v99
	v_max_f32_e32 v98, v98, v99
	v_xor_b32_e32 v99, 32, v220
	v_cmp_lt_i32_e32 vcc, v99, v100
	s_nop 1
	v_cndmask_b32_e32 v99, v220, v99, vcc
	v_lshlrev_b32_e32 v133, 2, v99
	v_mov_b32_e32 v99, v98
	s_nop 1
	v_permlane32_swap_b32_e32 v99, v98
	s_waitcnt lgkmcnt(0)
	v_max_f32_e32 v99, v99, v99
	v_max_f32_e32 v98, v98, v99
	v_cmp_gt_f32_e32 vcc, v98, v142
	s_cbranch_vccz .LBB0_219
	v_max_f32_e32 v98, v98, v98
	v_max_f32_e32 v99, v142, v142
	v_max_f32_e32 v106, v99, v98
	v_sub_f32_e32 v98, v142, v106
	v_exp_f32_e32 v118, v98
	v_mov_b32_e32 v107, v143
	v_mov_b32_e32 v141, v135
	v_mov_b64_e32 v[142:143], v[106:107]
	v_mul_f32_e32 v140, v134, v118
	v_pk_mul_f32 v[100:101], v[32:33], v[118:119] op_sel_hi:[1,0]
	v_pk_mul_f32 v[98:99], v[30:31], v[118:119] op_sel_hi:[1,0]
	v_pk_mul_f32 v[104:105], v[28:29], v[118:119] op_sel_hi:[1,0]
	v_pk_mul_f32 v[102:103], v[26:27], v[118:119] op_sel_hi:[1,0]
	v_pk_mul_f32 v[116:117], v[6:7], v[118:119] op_sel_hi:[1,0]
	v_pk_mul_f32 v[114:115], v[4:5], v[118:119] op_sel_hi:[1,0]
	v_pk_mul_f32 v[120:121], v[2:3], v[118:119] op_sel_hi:[1,0]
	v_pk_mul_f32 v[118:119], v[0:1], v[118:119] op_sel_hi:[1,0]
	s_branch .LBB0_220

.LBB0_220:
	v_sub_f32_e32 v107, v123, v106
	v_exp_f32_e32 v107, v107
	v_sub_f32_e32 v122, v122, v106
	v_exp_f32_e32 v122, v122
	v_sub_f32_e32 v113, v113, v106
	v_exp_f32_e32 v113, v113
	v_sub_f32_e32 v112, v112, v106
	v_exp_f32_e32 v112, v112
	v_sub_f32_e32 v111, v111, v106
	v_add_f32_e32 v123, 0, v107
	v_exp_f32_e32 v111, v111
	v_sub_f32_e32 v110, v110, v106
	v_add_f32_e32 v123, v122, v123
	v_exp_f32_e32 v110, v110
	v_sub_f32_e32 v109, v109, v106
	v_add_f32_e32 v123, v113, v123
	v_exp_f32_e32 v109, v109
	v_sub_f32_e32 v106, v108, v106
	v_add_f32_e32 v123, v112, v123
	v_exp_f32_e32 v106, v106
	v_add_f32_e32 v123, v111, v123
	v_add_f32_e32 v123, v110, v123
	v_add_f32_e32 v123, v109, v123
	v_add_f32_e32 v108, v106, v123
	v_cvt_pk_bf16_f32 v122, v107, v122
	v_cvt_pk_bf16_f32 v123, v113, v112
	v_cvt_pk_bf16_f32 v124, v111, v110
	v_cvt_pk_bf16_f32 v125, v109, v106
	v_add_f32_e32 v140, v140, v108
	s_waitcnt vmcnt(11)
	v_mfma_f32_16x16x32_bf16 v[110:113], v[42:45], v[122:125], v[98:101]
	s_waitcnt vmcnt(8)
	v_mfma_f32_16x16x32_bf16 v[98:101], v[34:37], v[122:125], v[118:121]
	s_nop 2
	v_mov_b32_e32 v118, v131
	v_mfma_f32_16x16x32_bf16 v[106:109], v[46:49], v[122:125], v[102:105]
	v_mfma_f32_16x16x32_bf16 v[102:105], v[38:41], v[122:125], v[114:117]
	s_nop 2
	ds_read_b128 v[114:117], v118
	ds_read_b128 v[118:121], v118 offset:64
	s_waitcnt lgkmcnt(1)
	v_mfma_f32_16x16x32_bf16 v[62:65], v[62:65], v[114:117], 0
	s_waitcnt lgkmcnt(0)
	v_mfma_f32_16x16x32_bf16 v[58:61], v[58:61], v[118:121], v[62:65]
	v_mfma_f32_16x16x32_bf16 v[62:65], v[66:69], v[114:117], 0
	v_mfma_f32_16x16x32_bf16 v[50:53], v[50:53], v[118:121], v[62:65]
	s_nop 5
	v_mul_f32_e32 v121, 0x3e38aa3b, v58
	v_mul_f32_e32 v120, 0x3e38aa3b, v59
	v_mul_f32_e32 v119, 0x3e38aa3b, v60
	v_mul_f32_e32 v118, 0x3e38aa3b, v61
	v_mul_f32_e32 v115, 0x3e38aa3b, v52
	v_mul_f32_e32 v114, 0x3e38aa3b, v53
	v_mul_f32_e32 v117, 0x3e38aa3b, v50
	v_mul_f32_e32 v116, 0x3e38aa3b, v51
	v_max_f32_e32 v52, v115, v114
	v_max_f32_e32 v50, v121, v120
	v_max_f32_e32 v51, v119, v118
	v_max3_f32 v52, v117, v116, v52
	v_max3_f32 v50, v50, v51, v52
	v_mov_b32_e32 v51, v50
	s_nop 1
	v_permlane16_swap_b32_e32 v51, v50
	s_waitcnt lgkmcnt(0)
	v_max_f32_e32 v51, v51, v51
	v_max_f32_e32 v50, v50, v51
	v_mov_b32_e32 v51, v50
	s_nop 1
	v_permlane32_swap_b32_e32 v51, v50
	s_waitcnt lgkmcnt(0)
	v_max_f32_e32 v51, v51, v51
	v_max_f32_e32 v50, v50, v51
	v_cmp_gt_f32_e32 vcc, v50, v143
	s_cbranch_vccz .LBB0_222
	v_max_f32_e32 v50, v50, v50
	v_max_f32_e32 v51, v143, v143
	v_max_f32_e32 v122, v51, v50
	v_sub_f32_e32 v50, v143, v122
	v_exp_f32_e32 v58, v50
	v_mov_b32_e32 v143, v122
	v_mul_f32_e32 v141, v141, v58
	v_pk_mul_f32 v[52:53], v[24:25], v[58:59] op_sel_hi:[1,0]
	v_pk_mul_f32 v[50:51], v[22:23], v[58:59] op_sel_hi:[1,0]
	v_pk_mul_f32 v[68:69], v[20:21], v[58:59] op_sel_hi:[1,0]
	v_pk_mul_f32 v[66:67], v[18:19], v[58:59] op_sel_hi:[1,0]
	v_pk_mul_f32 v[64:65], v[16:17], v[58:59] op_sel_hi:[1,0]
	v_pk_mul_f32 v[62:63], v[14:15], v[58:59] op_sel_hi:[1,0]
	v_pk_mul_f32 v[60:61], v[12:13], v[58:59] op_sel_hi:[1,0]
	v_pk_mul_f32 v[58:59], v[10:11], v[58:59] op_sel_hi:[1,0]
	s_branch .LBB0_223

.LBB0_223:
	v_sub_f32_e32 v121, v121, v122
	v_exp_f32_e32 v121, v121
	v_sub_f32_e32 v120, v120, v122
	v_exp_f32_e32 v120, v120
	v_sub_f32_e32 v119, v119, v122
	v_exp_f32_e32 v119, v119
	v_sub_f32_e32 v118, v118, v122
	v_exp_f32_e32 v118, v118
	v_sub_f32_e32 v117, v117, v122
	v_add_f32_e32 v123, 0, v121
	v_exp_f32_e32 v117, v117
	v_sub_f32_e32 v116, v116, v122
	v_add_f32_e32 v123, v120, v123
	v_exp_f32_e32 v116, v116
	v_sub_f32_e32 v115, v115, v122
	v_add_f32_e32 v123, v119, v123
	v_exp_f32_e32 v124, v115
	v_sub_f32_e32 v114, v114, v122
	v_add_f32_e32 v123, v118, v123
	v_exp_f32_e32 v122, v114
	v_add_f32_e32 v123, v117, v123
	s_cmpk_lg_i32 s28, 0x4000
	v_add_f32_e32 v123, v116, v123
	s_cselect_b32 s26, s28, 0x3000
	v_add_f32_e32 v115, v124, v123
	s_lshl_b64 s[0:1], s[26:27], 1
	v_add_f32_e32 v114, v122, v115
	v_lshl_add_u64 v[146:147], v[136:137], 0, s[0:1]
	v_add_f32_e32 v141, v141, v114
	v_cvt_pk_bf16_f32 v114, v121, v120
	v_cvt_pk_bf16_f32 v115, v119, v118
	v_cvt_pk_bf16_f32 v116, v117, v116
	v_cvt_pk_bf16_f32 v117, v124, v122
	v_lshl_add_u64 v[144:145], v[138:139], 0, s[0:1]
	v_mov_b32_e32 v148, v153
	v_mfma_f32_16x16x32_bf16 v[126:129], v[42:45], v[114:117], v[50:53]
	v_mfma_f32_16x16x32_bf16 v[122:125], v[46:49], v[114:117], v[66:69]
	v_mfma_f32_16x16x32_bf16 v[118:121], v[38:41], v[114:117], v[62:65]
	v_mfma_f32_16x16x32_bf16 v[114:117], v[34:37], v[114:117], v[58:61]
	s_nop 1
	global_load_dwordx4 v[62:65], v[146:147], off
	global_load_dwordx4 v[58:61], v[146:147], off offset:1024
	global_load_dwordx4 v[66:69], v[146:147], off offset:2048
	global_load_dwordx4 v[50:53], v[146:147], off offset:3072
	global_load_dwordx4 v[42:45], v[144:145], off
	global_load_dwordx4 v[46:49], v[144:145], off offset:1024
	global_load_dwordx4 v[38:41], v[144:145], off offset:2048
	global_load_dwordx4 v[34:37], v[144:145], off offset:3072
	ds_read_b128 v[156:159], v148
	ds_read_b128 v[160:163], v148 offset:64
	s_waitcnt vmcnt(15) lgkmcnt(1)
	v_mfma_f32_16x16x32_bf16 v[168:171], v[94:97], v[156:159], 0
	s_waitcnt vmcnt(13)
	v_mfma_f32_16x16x32_bf16 v[156:159], v[90:93], v[156:159], 0
	s_waitcnt vmcnt(12) lgkmcnt(0)
	v_mfma_f32_16x16x32_bf16 v[172:175], v[82:85], v[160:163], v[156:159]
	v_mfma_f32_16x16x32_bf16 v[168:171], v[86:89], v[160:163], v[168:171]
	s_nop 6
	v_mul_f32_e32 v156, 0x3e38aa3b, v174
	v_mul_f32_e32 v155, 0x3e38aa3b, v175
	v_mul_f32_e32 v162, 0x3e38aa3b, v168
	v_mul_f32_e32 v158, 0x3e38aa3b, v172
	v_mul_f32_e32 v161, 0x3e38aa3b, v169
	v_mul_f32_e32 v157, 0x3e38aa3b, v173
	v_mul_f32_e32 v160, 0x3e38aa3b, v170
	v_mul_f32_e32 v159, 0x3e38aa3b, v171
	v_max_f32_e32 v163, v156, v155
	v_max_f32_e32 v148, v162, v161
	v_max_f32_e32 v149, v160, v159
	v_max3_f32 v163, v158, v157, v163
	v_max3_f32 v148, v148, v149, v163
	v_mov_b32_e32 v149, v148
	s_nop 1
	v_permlane16_swap_b32_e32 v149, v148
	s_waitcnt lgkmcnt(0)
	v_max_f32_e32 v149, v149, v149
	v_max_f32_e32 v148, v148, v149
	v_mov_b32_e32 v149, v148
	s_nop 1
	v_permlane32_swap_b32_e32 v149, v148
	s_waitcnt lgkmcnt(0)
	v_max_f32_e32 v149, v149, v149
	v_max_f32_e32 v148, v148, v149
	v_cmp_gt_f32_e32 vcc, v148, v142
	s_cbranch_vccz .LBB0_225
	v_max_f32_e32 v148, v148, v148
	v_max_f32_e32 v149, v142, v142
	v_max_f32_e32 v148, v149, v148
	v_sub_f32_e32 v142, v142, v148
	v_exp_f32_e32 v142, v142
	v_mov_b32_e32 v149, v143
	v_mul_f32_e32 v140, v140, v142
	v_pk_mul_f32 v[112:113], v[112:113], v[142:143] op_sel_hi:[1,0]
	v_pk_mul_f32 v[110:111], v[110:111], v[142:143] op_sel_hi:[1,0]
	v_pk_mul_f32 v[108:109], v[108:109], v[142:143] op_sel_hi:[1,0]
	v_pk_mul_f32 v[106:107], v[106:107], v[142:143] op_sel_hi:[1,0]
	v_pk_mul_f32 v[104:105], v[104:105], v[142:143] op_sel_hi:[1,0]
	v_pk_mul_f32 v[102:103], v[102:103], v[142:143] op_sel_hi:[1,0]
	v_pk_mul_f32 v[100:101], v[100:101], v[142:143] op_sel_hi:[1,0]
	v_pk_mul_f32 v[98:99], v[98:99], v[142:143] op_sel_hi:[1,0]
	v_mov_b64_e32 v[142:143], v[148:149]
	s_branch .LBB0_226

.LBB0_226:
	v_sub_f32_e32 v149, v162, v148
	v_exp_f32_e32 v149, v149
	v_sub_f32_e32 v161, v161, v148
	v_exp_f32_e32 v161, v161
	v_sub_f32_e32 v160, v160, v148
	v_exp_f32_e32 v160, v160
	v_sub_f32_e32 v159, v159, v148
	v_exp_f32_e32 v159, v159
	v_sub_f32_e32 v158, v158, v148
	v_add_f32_e32 v162, 0, v149
	v_exp_f32_e32 v158, v158
	v_sub_f32_e32 v157, v157, v148
	v_add_f32_e32 v162, v161, v162
	v_exp_f32_e32 v163, v157
	v_add_f32_e32 v162, v160, v162
	v_add_f32_e32 v162, v159, v162
	v_add_f32_e32 v162, v158, v162
	v_sub_f32_e32 v156, v156, v148
	v_add_f32_e32 v157, v163, v162
	v_exp_f32_e32 v162, v156
	v_sub_f32_e32 v148, v155, v148
	v_exp_f32_e32 v148, v148
	v_cvt_pk_bf16_f32 v158, v158, v163
	v_add_f32_e32 v156, v162, v157
	v_cvt_pk_bf16_f32 v157, v160, v159
	v_add_f32_e32 v155, v148, v156
	v_cvt_pk_bf16_f32 v159, v162, v148
	v_mov_b32_e32 v148, v131
	v_cvt_pk_bf16_f32 v156, v149, v161
	v_add_f32_e32 v140, v140, v155
	s_waitcnt vmcnt(11)
	v_mfma_f32_16x16x32_bf16 v[110:113], v[78:81], v[156:159], v[110:113]
	s_waitcnt vmcnt(10)
	v_mfma_f32_16x16x32_bf16 v[106:109], v[74:77], v[156:159], v[106:109]
	s_waitcnt vmcnt(9)
	v_mfma_f32_16x16x32_bf16 v[102:105], v[70:73], v[156:159], v[102:105]
	s_waitcnt vmcnt(8)
	v_mfma_f32_16x16x32_bf16 v[98:101], v[54:57], v[156:159], v[98:101]
	ds_read_b128 v[156:159], v148
	ds_read_b128 v[160:163], v148 offset:64
	s_waitcnt lgkmcnt(1)
	v_mfma_f32_16x16x32_bf16 v[94:97], v[94:97], v[156:159], 0
	s_waitcnt lgkmcnt(0)
	v_mfma_f32_16x16x32_bf16 v[94:97], v[86:89], v[160:163], v[94:97]
	v_mfma_f32_16x16x32_bf16 v[86:89], v[90:93], v[156:159], 0
	v_mfma_f32_16x16x32_bf16 v[90:93], v[82:85], v[160:163], v[86:89]
	s_nop 6
	v_mul_f32_e32 v89, 0x3e38aa3b, v94
	v_mul_f32_e32 v83, 0x3e38aa3b, v92
	v_mul_f32_e32 v82, 0x3e38aa3b, v93
	v_mul_f32_e32 v85, 0x3e38aa3b, v90
	v_mul_f32_e32 v88, 0x3e38aa3b, v95
	v_mul_f32_e32 v84, 0x3e38aa3b, v91
	v_mul_f32_e32 v87, 0x3e38aa3b, v96
	v_mul_f32_e32 v86, 0x3e38aa3b, v97
	v_max_f32_e32 v92, v83, v82
	v_max_f32_e32 v90, v89, v88
	v_max_f32_e32 v91, v87, v86
	v_max3_f32 v92, v85, v84, v92
	v_max3_f32 v90, v90, v91, v92
	v_mov_b32_e32 v91, v90
	s_nop 1
	v_permlane16_swap_b32_e32 v91, v90
	s_waitcnt lgkmcnt(0)
	v_max_f32_e32 v91, v91, v91
	v_max_f32_e32 v90, v90, v91
	v_mov_b32_e32 v91, v90
	s_nop 1
	v_permlane32_swap_b32_e32 v91, v90
	s_waitcnt lgkmcnt(0)
	v_max_f32_e32 v91, v91, v91
	v_max_f32_e32 v90, v90, v91
	v_cmp_gt_f32_e32 vcc, v90, v143
	s_cbranch_vccnz .LBB0_213
	v_mov_b32_e32 v90, v143
	s_branch .LBB0_214

.LBB0_231:
	s_nop 4
	v_max_f32_e32 v106, v119, v119
	v_max_f32_e32 v107, v118, v118
	v_max_f32_e32 v106, v107, v106
	v_max_f32_e32 v107, v121, v121
	v_max_f32_e32 v108, v120, v120
	v_max_f32_e32 v107, v108, v107
	v_max_f32_e32 v108, v115, v115
	v_max_f32_e32 v109, v114, v114
	v_max_f32_e32 v108, v109, v108
	v_max3_f32 v108, v116, v117, v108
	v_max3_f32 v106, v106, v107, v108
	v_mov_b32_e32 v8, v106
	s_nop 1
	v_permlane16_swap_b32_e32 v8, v106
	s_waitcnt lgkmcnt(0)
	v_max_f32_e32 v8, v8, v8
	v_max_f32_e32 v8, v106, v8
	v_mov_b32_e32 v106, v8
	s_nop 1
	v_permlane32_swap_b32_e32 v106, v8
	s_waitcnt lgkmcnt(0)
	v_max_f32_e32 v106, v106, v106
	v_max_f32_e32 v8, v8, v106
	v_cmp_gt_f32_e32 vcc, v8, v153
	s_cbranch_vccz .LBB0_250
	v_max_f32_e32 v8, v8, v8
	v_max_f32_e32 v106, v153, v153
	v_max_f32_e32 v8, v106, v8
	v_sub_f32_e32 v106, v153, v8
	v_exp_f32_e32 v106, v106
	v_mov_b32_e32 v153, v8
	v_mul_f32_e32 v155, v155, v106
	v_pk_mul_f32 v[2:3], v[2:3], v[106:107] op_sel_hi:[1,0]
	v_pk_mul_f32 v[0:1], v[0:1], v[106:107] op_sel_hi:[1,0]
	v_pk_mul_f32 v[6:7], v[6:7], v[106:107] op_sel_hi:[1,0]
	v_pk_mul_f32 v[4:5], v[4:5], v[106:107] op_sel_hi:[1,0]
	v_pk_mul_f32 v[124:125], v[124:125], v[106:107] op_sel_hi:[1,0]
	v_pk_mul_f32 v[122:123], v[122:123], v[106:107] op_sel_hi:[1,0]
	v_pk_mul_f32 v[128:129], v[128:129], v[106:107] op_sel_hi:[1,0]
	v_pk_mul_f32 v[126:127], v[126:127], v[106:107] op_sel_hi:[1,0]

.LBB0_245:
	s_nop 0
	v_max_f32_e32 v8, v1, v1
	v_max_f32_e32 v90, v0, v0
	v_max_f32_e32 v8, v90, v8
	v_max_f32_e32 v90, v3, v3
	v_max_f32_e32 v91, v2, v2
	v_max_f32_e32 v90, v91, v90
	v_max_f32_e32 v91, v7, v7
	v_max_f32_e32 v92, v6, v6
	v_max_f32_e32 v91, v92, v91
	v_max3_f32 v91, v4, v5, v91
	v_max3_f32 v90, v8, v90, v91
	v_and_b32_e32 v91, 64, v220
	v_xor_b32_e32 v8, 16, v220
	v_add_u32_e32 v91, 64, v91
	v_cmp_lt_i32_e32 vcc, v8, v91
	s_nop 1
	v_cndmask_b32_e32 v8, v220, v8, vcc
	v_lshlrev_b32_e32 v8, 2, v8
	v_mov_b32_e32 v92, v90
	s_nop 1
	v_permlane16_swap_b32_e32 v92, v90
	s_waitcnt lgkmcnt(0)
	v_max_f32_e32 v92, v92, v92
	v_max_f32_e32 v90, v90, v92
	v_xor_b32_e32 v92, 32, v220
	v_cmp_lt_i32_e32 vcc, v92, v91
	s_nop 1
	v_cndmask_b32_e32 v91, v220, v92, vcc
	v_lshlrev_b32_e32 v171, 2, v91
	v_mov_b32_e32 v91, v90
	s_nop 1
	v_permlane32_swap_b32_e32 v91, v90
	s_waitcnt lgkmcnt(0)
	v_max_f32_e32 v91, v91, v91
	v_max_f32_e32 v90, v90, v91
	v_cmp_gt_f32_e32 vcc, v90, v152
	s_cbranch_vccz .LBB0_251
	v_max_f32_e32 v90, v90, v90
	v_max_f32_e32 v91, v152, v152
	v_max_f32_e32 v122, v91, v90
	v_sub_f32_e32 v90, v152, v122
	v_exp_f32_e32 v102, v90
	v_mov_b32_e32 v123, v153
	v_mov_b32_e32 v155, v139
	v_mov_b64_e32 v[152:153], v[122:123]
	v_mul_f32_e32 v154, v138, v102
	v_pk_mul_f32 v[92:93], v[40:41], v[102:103] op_sel_hi:[1,0]
	v_pk_mul_f32 v[90:91], v[38:39], v[102:103] op_sel_hi:[1,0]
	v_pk_mul_f32 v[96:97], v[36:37], v[102:103] op_sel_hi:[1,0]
	v_pk_mul_f32 v[94:95], v[34:35], v[102:103] op_sel_hi:[1,0]
	v_pk_mul_f32 v[100:101], v[32:33], v[102:103] op_sel_hi:[1,0]
	v_pk_mul_f32 v[98:99], v[30:31], v[102:103] op_sel_hi:[1,0]
	v_pk_mul_f32 v[104:105], v[28:29], v[102:103] op_sel_hi:[1,0]
	v_pk_mul_f32 v[102:103], v[26:27], v[102:103] op_sel_hi:[1,0]
	s_branch .LBB0_252

.LBB0_257:
	s_nop 3
	v_max_f32_e32 v74, v1, v1
	v_max_f32_e32 v75, v0, v0
	v_max_f32_e32 v74, v75, v74
	v_max_f32_e32 v75, v3, v3
	v_max_f32_e32 v76, v2, v2
	v_max_f32_e32 v75, v76, v75
	v_max_f32_e32 v76, v7, v7
	v_max_f32_e32 v77, v6, v6
	v_max_f32_e32 v76, v77, v76
	v_max3_f32 v76, v4, v5, v76
	v_max3_f32 v74, v74, v75, v76
	v_mov_b32_e32 v75, v74
	s_nop 1
	v_permlane16_swap_b32_e32 v75, v74
	s_waitcnt lgkmcnt(0)
	v_max_f32_e32 v75, v75, v75
	v_max_f32_e32 v74, v74, v75
	v_mov_b32_e32 v75, v74
	s_nop 1
	v_permlane32_swap_b32_e32 v75, v74
	s_waitcnt lgkmcnt(0)
	v_max_f32_e32 v75, v75, v75
	v_max_f32_e32 v74, v74, v75
	v_cmp_gt_f32_e32 vcc, v74, v153
	s_cbranch_vccz .LBB0_260
	v_max_f32_e32 v74, v74, v74
	v_max_f32_e32 v75, v153, v153
	v_max_f32_e32 v122, v75, v74
	v_sub_f32_e32 v74, v153, v122
	v_exp_f32_e32 v74, v74
	v_mov_b32_e32 v153, v122
	v_mul_f32_e32 v155, v155, v74
	v_pk_mul_f32 v[88:89], v[24:25], v[74:75] op_sel_hi:[1,0]
	v_pk_mul_f32 v[86:87], v[22:23], v[74:75] op_sel_hi:[1,0]
	v_pk_mul_f32 v[84:85], v[20:21], v[74:75] op_sel_hi:[1,0]
	v_pk_mul_f32 v[82:83], v[18:19], v[74:75] op_sel_hi:[1,0]
	v_pk_mul_f32 v[80:81], v[16:17], v[74:75] op_sel_hi:[1,0]
	v_pk_mul_f32 v[78:79], v[14:15], v[74:75] op_sel_hi:[1,0]
	v_pk_mul_f32 v[76:77], v[12:13], v[74:75] op_sel_hi:[1,0]
	v_pk_mul_f32 v[74:75], v[10:11], v[74:75] op_sel_hi:[1,0]
	s_branch .LBB0_261

.LBB0_269:
	s_nop 2
	v_max_f32_e32 v130, v161, v161
	v_max_f32_e32 v131, v160, v160
	v_max_f32_e32 v130, v131, v130
	v_max_f32_e32 v131, v163, v163
	v_max_f32_e32 v132, v162, v162
	v_max_f32_e32 v131, v132, v131
	v_max_f32_e32 v132, v157, v157
	v_max_f32_e32 v133, v156, v156
	v_max_f32_e32 v132, v133, v132
	v_max3_f32 v132, v158, v159, v132
	v_max3_f32 v130, v130, v131, v132
	v_mov_b32_e32 v131, v130
	s_nop 1
	v_permlane16_swap_b32_e32 v131, v130
	s_waitcnt lgkmcnt(0)
	v_max_f32_e32 v131, v131, v131
	v_max_f32_e32 v130, v130, v131
	v_mov_b32_e32 v131, v130
	s_nop 1
	v_permlane32_swap_b32_e32 v131, v130
	s_waitcnt lgkmcnt(0)
	v_max_f32_e32 v131, v131, v131
	v_max_f32_e32 v130, v130, v131
	v_cmp_gt_f32_e32 vcc, v130, v152
	s_cbranch_vccz .LBB0_271
	v_max_f32_e32 v130, v130, v130
	v_max_f32_e32 v131, v152, v152
	v_max_f32_e32 v130, v131, v130
	v_sub_f32_e32 v131, v152, v130
	v_exp_f32_e32 v132, v131
	v_mov_b32_e32 v131, v153
	v_mov_b64_e32 v[152:153], v[130:131]
	v_mul_f32_e32 v154, v154, v132
	v_pk_mul_f32 v[92:93], v[92:93], v[132:133] op_sel_hi:[1,0]
	v_pk_mul_f32 v[90:91], v[90:91], v[132:133] op_sel_hi:[1,0]
	v_pk_mul_f32 v[96:97], v[96:97], v[132:133] op_sel_hi:[1,0]
	v_pk_mul_f32 v[94:95], v[94:95], v[132:133] op_sel_hi:[1,0]
	v_pk_mul_f32 v[100:101], v[100:101], v[132:133] op_sel_hi:[1,0]
	v_pk_mul_f32 v[98:99], v[98:99], v[132:133] op_sel_hi:[1,0]
	v_pk_mul_f32 v[104:105], v[104:105], v[132:133] op_sel_hi:[1,0]
	v_pk_mul_f32 v[102:103], v[102:103], v[132:133] op_sel_hi:[1,0]
	s_branch .LBB0_272
